# P7-idle in-projection weight transposes: norm-scale vector loaded before the 64 tile loads, full drain replaced by counted in-order waits per element
# baseline (speedup 1.0000x reference)
.LBB0_1635:
	s_or_b64 exec, exec, s[0:1]
	v_max_i32_e32 v0, 0, v0
	v_lshl_add_u64 v[12:13], v[0:1], 2, s[26:27]
	s_lshl_b32 s0, s10, 6
	v_mad_i64_i32 v[12:13], s[4:5], s0, v227, v[12:13]
	s_ashr_i32 s1, s0, 31
	v_cmp_ne_u32_e64 s[100:101], 1, v223
	s_nop 1
	s_and_b64 vcc, exec, s[100:101]
	s_cbranch_vccnz .Lwjc_noscale
	s_lshl_b64 s[4:5], s[0:1], 2
	s_add_u32 s4, s37, s4
	s_addc_u32 s5, s33, s5
	v_lshlrev_b32_e32 v101, 2, v46
	global_load_dword v100, v101, s[4:5]
.Lwjc_noscale:
	v_add_co_u32_e32 v14, vcc, 0xc000, v12
	s_mov_b32 s4, 0x86000
	s_nop 0
	v_addc_co_u32_e32 v15, vcc, 0, v13, vcc
	global_load_dword v85, v[14:15], off offset:1088
	v_add_co_u32_e32 v14, vcc, s9, v12
	global_load_dword v86, v[12:13], off
	s_nop 0
	v_addc_co_u32_e32 v15, vcc, 0, v13, vcc
	global_load_dword v84, v[14:15], off offset:2176
	v_add_co_u32_e32 v14, vcc, 0x24000, v12
	v_cmp_lt_i32_e64 s[40:41], -1, v66
	s_nop 0
	v_addc_co_u32_e32 v15, vcc, 0, v13, vcc
	global_load_dword v83, v[14:15], off offset:3264
	v_add_co_u32_e32 v14, vcc, 0x31000, v12
	v_cmp_ne_u32_e64 s[42:43], 1, v223
	s_nop 0
	v_addc_co_u32_e32 v15, vcc, 0, v13, vcc
	global_load_dword v82, v[14:15], off offset:256
	v_add_co_u32_e32 v14, vcc, 0x3d000, v12
	s_ashr_i32 s1, s0, 31
	s_nop 0
	v_addc_co_u32_e32 v15, vcc, 0, v13, vcc
	global_load_dword v80, v[14:15], off offset:1344
	v_add_co_u32_e32 v14, vcc, 0x49000, v12
	s_nop 1
	v_addc_co_u32_e32 v15, vcc, 0, v13, vcc
	global_load_dword v78, v[14:15], off offset:2432
	v_add_co_u32_e32 v14, vcc, 0x55000, v12
	s_nop 1
	v_addc_co_u32_e32 v15, vcc, 0, v13, vcc
	global_load_dword v81, v[14:15], off offset:3520
	v_add_co_u32_e32 v14, vcc, s21, v12
	s_nop 1
	v_addc_co_u32_e32 v15, vcc, 0, v13, vcc
	global_load_dword v79, v[14:15], off offset:512
	v_add_co_u32_e32 v14, vcc, s16, v12
	s_nop 1
	v_addc_co_u32_e32 v15, vcc, 0, v13, vcc
	global_load_dword v77, v[14:15], off offset:1600
	v_add_co_u32_e32 v14, vcc, s89, v12
	s_nop 1
	v_addc_co_u32_e32 v15, vcc, 0, v13, vcc
	global_load_dword v76, v[14:15], off offset:2688
	v_add_co_u32_e32 v14, vcc, s4, v12
	s_mov_b32 s4, 0x93000
	s_nop 0
	v_addc_co_u32_e32 v15, vcc, 0, v13, vcc
	global_load_dword v75, v[14:15], off offset:3776
	v_add_co_u32_e32 v14, vcc, s4, v12
	s_mov_b32 s4, 0x9f000
	s_nop 0
	v_addc_co_u32_e32 v15, vcc, 0, v13, vcc
	global_load_dword v74, v[14:15], off offset:768
	v_add_co_u32_e32 v14, vcc, s4, v12
	s_mov_b32 s4, 0xab000
	s_nop 0
	v_addc_co_u32_e32 v15, vcc, 0, v13, vcc
	global_load_dword v72, v[14:15], off offset:1856
	v_add_co_u32_e32 v14, vcc, s4, v12
	s_mov_b32 s4, 0xb7000
	s_nop 0
	v_addc_co_u32_e32 v15, vcc, 0, v13, vcc
	global_load_dword v70, v[14:15], off offset:2944
	v_add_co_u32_e32 v14, vcc, s4, v12
	s_mov_b32 s4, 0xc4000
	s_nop 0
	v_addc_co_u32_e32 v15, vcc, 0, v13, vcc
	global_load_dword v73, v[14:15], off offset:4032
	v_add_co_u32_e32 v14, vcc, s4, v12
	s_mov_b32 s4, 0xd0000
	s_nop 0
	v_addc_co_u32_e32 v15, vcc, 0, v13, vcc
	global_load_dword v71, v[14:15], off offset:1024
	v_add_co_u32_e32 v14, vcc, s4, v12
	s_mov_b32 s4, 0xdc000
	s_nop 0
	v_addc_co_u32_e32 v15, vcc, 0, v13, vcc
	global_load_dword v69, v[14:15], off offset:2112
	v_add_co_u32_e32 v14, vcc, s4, v12
	s_mov_b32 s4, 0xe9000
	s_nop 0
	v_addc_co_u32_e32 v15, vcc, 0, v13, vcc
	global_load_dword v68, v[14:15], off offset:3200
	v_add_co_u32_e32 v14, vcc, s4, v12
	s_mov_b32 s4, 0xf5000
	s_nop 0
	v_addc_co_u32_e32 v15, vcc, 0, v13, vcc
	global_load_dword v67, v[14:15], off offset:192
	v_add_co_u32_e32 v14, vcc, s4, v12
	s_mov_b32 s4, 0x101000
	s_nop 0
	v_addc_co_u32_e32 v15, vcc, 0, v13, vcc
	global_load_dword v65, v[14:15], off offset:1280
	v_add_co_u32_e32 v14, vcc, s4, v12
	s_mov_b32 s4, 0x10d000
	s_nop 0
	v_addc_co_u32_e32 v15, vcc, 0, v13, vcc
	global_load_dword v63, v[14:15], off offset:2368
	v_add_co_u32_e32 v14, vcc, s4, v12
	s_mov_b32 s4, 0x11a000
	s_nop 0
	v_addc_co_u32_e32 v15, vcc, 0, v13, vcc
	global_load_dword v61, v[14:15], off offset:3456
	v_add_co_u32_e32 v14, vcc, s4, v12
	s_mov_b32 s4, 0x126000
	s_nop 0
	v_addc_co_u32_e32 v15, vcc, 0, v13, vcc
	global_load_dword v64, v[14:15], off offset:448
	v_add_co_u32_e32 v14, vcc, s4, v12
	s_mov_b32 s4, 0x132000
	s_nop 0
	v_addc_co_u32_e32 v15, vcc, 0, v13, vcc
	global_load_dword v62, v[14:15], off offset:1536
	v_add_co_u32_e32 v14, vcc, s4, v12
	s_mov_b32 s4, 0x13e000
	s_nop 0
	v_addc_co_u32_e32 v15, vcc, 0, v13, vcc
	global_load_dword v60, v[14:15], off offset:2624
	v_add_co_u32_e32 v14, vcc, s4, v12
	s_mov_b32 s4, 0x14b000
	s_nop 0
	v_addc_co_u32_e32 v15, vcc, 0, v13, vcc
	global_load_dword v59, v[14:15], off offset:3712
	v_add_co_u32_e32 v14, vcc, s4, v12
	s_mov_b32 s4, 0x157000
	s_nop 0
	v_addc_co_u32_e32 v15, vcc, 0, v13, vcc
	global_load_dword v58, v[14:15], off offset:704
	v_add_co_u32_e32 v14, vcc, s4, v12
	s_mov_b32 s4, 0x163000
	s_nop 0
	v_addc_co_u32_e32 v15, vcc, 0, v13, vcc
	global_load_dword v57, v[14:15], off offset:1792
	v_add_co_u32_e32 v14, vcc, s4, v12
	s_mov_b32 s4, 0x16f000
	s_nop 0
	v_addc_co_u32_e32 v15, vcc, 0, v13, vcc
	global_load_dword v44, v[14:15], off offset:2880
	v_add_co_u32_e32 v14, vcc, s4, v12
	s_mov_b32 s4, 0x17c000
	s_nop 0
	v_addc_co_u32_e32 v15, vcc, 0, v13, vcc
	global_load_dword v42, v[14:15], off offset:3968
	v_add_co_u32_e32 v14, vcc, s4, v12
	s_mov_b32 s4, 0x188000
	s_nop 0
	v_addc_co_u32_e32 v15, vcc, 0, v13, vcc
	global_load_dword v45, v[14:15], off offset:960
	v_add_co_u32_e32 v14, vcc, s4, v12
	s_mov_b32 s4, 0x194000
	s_nop 0
	v_addc_co_u32_e32 v15, vcc, 0, v13, vcc
	global_load_dword v43, v[14:15], off offset:2048
	v_add_co_u32_e32 v14, vcc, s4, v12
	s_mov_b32 s4, 0x1a1000
	s_nop 0
	v_addc_co_u32_e32 v15, vcc, 0, v13, vcc
	global_load_dword v41, v[14:15], off offset:3136
	v_add_co_u32_e32 v14, vcc, s4, v12
	s_mov_b32 s4, 0x1ad000
	s_nop 0
	v_addc_co_u32_e32 v15, vcc, 0, v13, vcc
	global_load_dword v40, v[14:15], off offset:128
	v_add_co_u32_e32 v14, vcc, s4, v12
	s_mov_b32 s4, 0x1b9000
	s_nop 0
	v_addc_co_u32_e32 v15, vcc, 0, v13, vcc
	global_load_dword v39, v[14:15], off offset:1216
	v_add_co_u32_e32 v14, vcc, s4, v12
	s_mov_b32 s4, 0x1c5000
	s_nop 0
	v_addc_co_u32_e32 v15, vcc, 0, v13, vcc
	global_load_dword v38, v[14:15], off offset:2304
	v_add_co_u32_e32 v14, vcc, s4, v12
	s_mov_b32 s4, 0x1d2000
	s_nop 0
	v_addc_co_u32_e32 v15, vcc, 0, v13, vcc
	global_load_dword v36, v[14:15], off offset:3392
	v_add_co_u32_e32 v14, vcc, s4, v12
	s_mov_b32 s4, 0x1de000
	s_nop 0
	v_addc_co_u32_e32 v15, vcc, 0, v13, vcc
	global_load_dword v34, v[14:15], off offset:384
	v_add_co_u32_e32 v14, vcc, s4, v12
	s_mov_b32 s4, 0x1ea000
	s_nop 0
	v_addc_co_u32_e32 v15, vcc, 0, v13, vcc
	global_load_dword v37, v[14:15], off offset:1472
	v_add_co_u32_e32 v14, vcc, s4, v12
	s_mov_b32 s4, 0x1f6000
	s_nop 0
	v_addc_co_u32_e32 v15, vcc, 0, v13, vcc
	global_load_dword v35, v[14:15], off offset:2560
	v_add_co_u32_e32 v14, vcc, s4, v12
	s_mov_b32 s4, 0x203000
	s_nop 0
	v_addc_co_u32_e32 v15, vcc, 0, v13, vcc
	global_load_dword v33, v[14:15], off offset:3648
	v_add_co_u32_e32 v14, vcc, s4, v12
	s_mov_b32 s4, 0x20f000
	s_nop 0
	v_addc_co_u32_e32 v15, vcc, 0, v13, vcc
	global_load_dword v32, v[14:15], off offset:640
	v_add_co_u32_e32 v14, vcc, s4, v12
	s_mov_b32 s4, 0x21b000
	s_nop 0
	v_addc_co_u32_e32 v15, vcc, 0, v13, vcc
	global_load_dword v31, v[14:15], off offset:1728
	v_add_co_u32_e32 v14, vcc, s4, v12
	s_mov_b32 s4, 0x227000
	s_nop 0
	v_addc_co_u32_e32 v15, vcc, 0, v13, vcc
	global_load_dword v30, v[14:15], off offset:2816
	v_add_co_u32_e32 v14, vcc, s4, v12
	s_mov_b32 s4, 0x234000
	s_nop 0
	v_addc_co_u32_e32 v15, vcc, 0, v13, vcc
	global_load_dword v28, v[14:15], off offset:3904
	v_add_co_u32_e32 v14, vcc, s4, v12
	s_mov_b32 s4, 0x240000
	s_nop 0
	v_addc_co_u32_e32 v15, vcc, 0, v13, vcc
	global_load_dword v26, v[14:15], off offset:896
	v_add_co_u32_e32 v14, vcc, s4, v12
	s_mov_b32 s4, 0x24c000
	s_nop 0
	v_addc_co_u32_e32 v15, vcc, 0, v13, vcc
	global_load_dword v29, v[14:15], off offset:1984
	v_add_co_u32_e32 v14, vcc, s4, v12
	s_mov_b32 s4, 0x259000
	s_nop 0
	v_addc_co_u32_e32 v15, vcc, 0, v13, vcc
	global_load_dword v27, v[14:15], off offset:3072
	v_add_co_u32_e32 v14, vcc, s4, v12
	s_mov_b32 s4, 0x265000
	s_nop 0
	v_addc_co_u32_e32 v15, vcc, 0, v13, vcc
	global_load_dword v25, v[14:15], off offset:64
	v_add_co_u32_e32 v14, vcc, s4, v12
	s_mov_b32 s4, 0x271000
	s_nop 0
	v_addc_co_u32_e32 v15, vcc, 0, v13, vcc
	global_load_dword v24, v[14:15], off offset:1152
	v_add_co_u32_e32 v14, vcc, s4, v12
	s_mov_b32 s4, 0x27d000
	s_nop 0
	v_addc_co_u32_e32 v15, vcc, 0, v13, vcc
	global_load_dword v23, v[14:15], off offset:2240
	v_add_co_u32_e32 v14, vcc, s4, v12
	s_mov_b32 s4, 0x28a000
	s_nop 0
	v_addc_co_u32_e32 v15, vcc, 0, v13, vcc
	global_load_dword v22, v[14:15], off offset:3328
	v_add_co_u32_e32 v14, vcc, s4, v12
	s_mov_b32 s4, 0x296000
	s_nop 0
	v_addc_co_u32_e32 v15, vcc, 0, v13, vcc
	global_load_dword v20, v[14:15], off offset:320
	v_add_co_u32_e32 v14, vcc, s4, v12
	s_mov_b32 s4, 0x2a2000
	s_nop 0
	v_addc_co_u32_e32 v15, vcc, 0, v13, vcc
	global_load_dword v18, v[14:15], off offset:1408
	v_add_co_u32_e32 v14, vcc, s4, v12
	s_mov_b32 s4, 0x2ae000
	s_nop 0
	v_addc_co_u32_e32 v15, vcc, 0, v13, vcc
	global_load_dword v21, v[14:15], off offset:2496
	v_add_co_u32_e32 v14, vcc, s4, v12
	s_mov_b32 s4, 0x2bb000
	s_nop 0
	v_addc_co_u32_e32 v15, vcc, 0, v13, vcc
	global_load_dword v19, v[14:15], off offset:3584
	v_add_co_u32_e32 v14, vcc, s4, v12
	s_mov_b32 s4, 0x2c7000
	s_nop 0
	v_addc_co_u32_e32 v15, vcc, 0, v13, vcc
	global_load_dword v17, v[14:15], off offset:576
	v_add_co_u32_e32 v14, vcc, s4, v12
	s_mov_b32 s4, 0x2d3000
	s_nop 0
	v_addc_co_u32_e32 v15, vcc, 0, v13, vcc
	global_load_dword v16, v[14:15], off offset:1664
	v_add_co_u32_e32 v14, vcc, s4, v12
	s_mov_b32 s4, 0x2df000
	s_nop 0
	v_addc_co_u32_e32 v15, vcc, 0, v13, vcc
	v_add_co_u32_e32 v88, vcc, s4, v12
	global_load_dword v15, v[14:15], off offset:2752
	s_nop 0
	v_addc_co_u32_e32 v89, vcc, 0, v13, vcc
	global_load_dword v14, v[88:89], off offset:3840
	v_add_co_u32_e32 v88, vcc, 0x2ec000, v12
	s_nop 1
	v_addc_co_u32_e32 v89, vcc, 0, v13, vcc
	global_load_dword v11, v[88:89], off offset:832
	v_add_co_u32_e32 v88, vcc, 0x2f8000, v12
	s_nop 1
	v_addc_co_u32_e32 v89, vcc, 0, v13, vcc
	v_add_co_u32_e32 v12, vcc, 0x304000, v12
	global_load_dword v0, v[88:89], off offset:1920
	s_nop 0
	v_addc_co_u32_e32 v13, vcc, 0, v13, vcc
	global_load_dword v12, v[12:13], off offset:3008
	s_waitcnt vmcnt(62)
	v_cndmask_b32_e64 v13, 0, v86, s[40:41]
	s_and_b64 vcc, exec, s[42:43]
	s_cbranch_vccnz .LBB0_1637
	v_readlane_b32 s4, v100, 0
	s_nop 1
	v_mul_f32_e32 v13, s4, v13

.LBB0_1639:
	ds_write_b32 v47, v13 offset:260
	s_and_b64 vcc, exec, s[42:43]
	s_waitcnt vmcnt(61)
	v_cndmask_b32_e64 v13, 0, v84, s[40:41]
	s_cbranch_vccnz .LBB0_1641
	v_readlane_b32 s4, v100, 2
	s_nop 1
	v_mul_f32_e32 v13, s4, v13
.LBB0_1641:
	ds_write_b32 v47, v13 offset:520
	s_and_b64 vcc, exec, s[42:43]
	s_waitcnt vmcnt(60)
	v_cndmask_b32_e64 v13, 0, v83, s[40:41]
	s_cbranch_vccnz .LBB0_1643
	v_readlane_b32 s4, v100, 3
	s_nop 1
	v_mul_f32_e32 v13, s4, v13
.LBB0_1643:
	ds_write_b32 v47, v13 offset:780
	s_and_b64 vcc, exec, s[42:43]
	s_waitcnt vmcnt(59)
	v_cndmask_b32_e64 v13, 0, v82, s[40:41]
	s_cbranch_vccnz .LBB0_1645
	v_readlane_b32 s4, v100, 4
	s_nop 1
	v_mul_f32_e32 v13, s4, v13
.LBB0_1645:
	ds_write_b32 v47, v13 offset:1040
	s_and_b64 vcc, exec, s[42:43]
	s_waitcnt vmcnt(58)
	v_cndmask_b32_e64 v13, 0, v80, s[40:41]
	s_cbranch_vccnz .LBB0_1647
	v_readlane_b32 s4, v100, 5
	s_nop 1
	v_mul_f32_e32 v13, s4, v13
.LBB0_1647:
	ds_write_b32 v47, v13 offset:1300
	s_and_b64 vcc, exec, s[42:43]
	s_waitcnt vmcnt(57)
	v_cndmask_b32_e64 v13, 0, v78, s[40:41]
	s_cbranch_vccnz .LBB0_1649
	v_readlane_b32 s4, v100, 6
	s_nop 1
	v_mul_f32_e32 v13, s4, v13
.LBB0_1649:
	ds_write_b32 v47, v13 offset:1560
	s_and_b64 vcc, exec, s[42:43]
	s_waitcnt vmcnt(56)
	v_cndmask_b32_e64 v13, 0, v81, s[40:41]
	s_cbranch_vccnz .LBB0_1651
	v_readlane_b32 s4, v100, 7
	s_nop 1
	v_mul_f32_e32 v13, s4, v13
.LBB0_1651:
	ds_write_b32 v47, v13 offset:1820
	s_and_b64 vcc, exec, s[42:43]
	s_waitcnt vmcnt(55)
	v_cndmask_b32_e64 v13, 0, v79, s[40:41]
	s_cbranch_vccnz .LBB0_1653
	v_readlane_b32 s4, v100, 8
	s_nop 1
	v_mul_f32_e32 v13, s4, v13
.LBB0_1653:
	ds_write_b32 v47, v13 offset:2080
	s_and_b64 vcc, exec, s[42:43]
	s_waitcnt vmcnt(54)
	v_cndmask_b32_e64 v13, 0, v77, s[40:41]
	s_cbranch_vccnz .LBB0_1655
	v_readlane_b32 s4, v100, 9
	s_nop 1
	v_mul_f32_e32 v13, s4, v13
.LBB0_1655:
	ds_write_b32 v47, v13 offset:2340
	s_and_b64 vcc, exec, s[42:43]
	s_waitcnt vmcnt(53)
	v_cndmask_b32_e64 v13, 0, v76, s[40:41]
	s_cbranch_vccnz .LBB0_1657
	v_readlane_b32 s4, v100, 10
	s_nop 1
	v_mul_f32_e32 v13, s4, v13
.LBB0_1657:
	ds_write_b32 v47, v13 offset:2600
	s_and_b64 vcc, exec, s[42:43]
	s_waitcnt vmcnt(52)
	v_cndmask_b32_e64 v13, 0, v75, s[40:41]
	s_cbranch_vccnz .LBB0_1659
	v_readlane_b32 s4, v100, 11
	s_nop 1
	v_mul_f32_e32 v13, s4, v13
.LBB0_1659:
	ds_write_b32 v47, v13 offset:2860
	s_and_b64 vcc, exec, s[42:43]
	s_waitcnt vmcnt(51)
	v_cndmask_b32_e64 v13, 0, v74, s[40:41]
	s_cbranch_vccnz .LBB0_1661
	v_readlane_b32 s4, v100, 12
	s_nop 1
	v_mul_f32_e32 v13, s4, v13
.LBB0_1661:
	ds_write_b32 v47, v13 offset:3120
	s_and_b64 vcc, exec, s[42:43]
	s_waitcnt vmcnt(50)
	v_cndmask_b32_e64 v13, 0, v72, s[40:41]
	s_cbranch_vccnz .LBB0_1663
	v_readlane_b32 s4, v100, 13
	s_nop 1
	v_mul_f32_e32 v13, s4, v13
.LBB0_1663:
	ds_write_b32 v47, v13 offset:3380
	s_and_b64 vcc, exec, s[42:43]
	s_waitcnt vmcnt(49)
	v_cndmask_b32_e64 v13, 0, v70, s[40:41]
	s_cbranch_vccnz .LBB0_1665
	v_readlane_b32 s4, v100, 14
	s_nop 1
	v_mul_f32_e32 v13, s4, v13
.LBB0_1665:
	ds_write_b32 v47, v13 offset:3640
	s_and_b64 vcc, exec, s[42:43]
	s_waitcnt vmcnt(48)
	v_cndmask_b32_e64 v13, 0, v73, s[40:41]
	s_cbranch_vccnz .LBB0_1667
	v_readlane_b32 s4, v100, 15
	s_nop 1
	v_mul_f32_e32 v13, s4, v13
.LBB0_1667:
	ds_write_b32 v47, v13 offset:3900
	s_and_b64 vcc, exec, s[42:43]
	s_waitcnt vmcnt(47)
	v_cndmask_b32_e64 v13, 0, v71, s[40:41]
	s_cbranch_vccnz .LBB0_1669
	v_readlane_b32 s4, v100, 16
	s_nop 1
	v_mul_f32_e32 v13, s4, v13
.LBB0_1669:
	ds_write_b32 v47, v13 offset:4160
	s_and_b64 vcc, exec, s[42:43]
	s_waitcnt vmcnt(46)
	v_cndmask_b32_e64 v13, 0, v69, s[40:41]
	s_cbranch_vccnz .LBB0_1671
	v_readlane_b32 s4, v100, 17
	s_nop 1
	v_mul_f32_e32 v13, s4, v13
.LBB0_1671:
	ds_write_b32 v47, v13 offset:4420
	s_and_b64 vcc, exec, s[42:43]
	s_waitcnt vmcnt(45)
	v_cndmask_b32_e64 v13, 0, v68, s[40:41]
	s_cbranch_vccnz .LBB0_1673
	v_readlane_b32 s4, v100, 18
	s_nop 1
	v_mul_f32_e32 v13, s4, v13
.LBB0_1673:
	ds_write_b32 v47, v13 offset:4680
	s_and_b64 vcc, exec, s[42:43]
	s_waitcnt vmcnt(44)
	v_cndmask_b32_e64 v13, 0, v67, s[40:41]
	s_cbranch_vccnz .LBB0_1675
	v_readlane_b32 s4, v100, 19
	s_nop 1
	v_mul_f32_e32 v13, s4, v13
.LBB0_1675:
	ds_write_b32 v47, v13 offset:4940
	s_and_b64 vcc, exec, s[42:43]
	s_waitcnt vmcnt(43)
	v_cndmask_b32_e64 v13, 0, v65, s[40:41]
	s_cbranch_vccnz .LBB0_1677
	v_readlane_b32 s4, v100, 20
	s_nop 1
	v_mul_f32_e32 v13, s4, v13
.LBB0_1677:
	ds_write_b32 v47, v13 offset:5200
	s_and_b64 vcc, exec, s[42:43]
	s_waitcnt vmcnt(42)
	v_cndmask_b32_e64 v13, 0, v63, s[40:41]
	s_cbranch_vccnz .LBB0_1679
	v_readlane_b32 s4, v100, 21
	s_nop 1
	v_mul_f32_e32 v13, s4, v13
.LBB0_1679:
	ds_write_b32 v47, v13 offset:5460
	s_and_b64 vcc, exec, s[42:43]
	s_waitcnt vmcnt(41)
	v_cndmask_b32_e64 v13, 0, v61, s[40:41]
	s_cbranch_vccnz .LBB0_1681
	v_readlane_b32 s4, v100, 22
	s_nop 1
	v_mul_f32_e32 v13, s4, v13
.LBB0_1681:
	ds_write_b32 v47, v13 offset:5720
	s_and_b64 vcc, exec, s[42:43]
	s_waitcnt vmcnt(40)
	v_cndmask_b32_e64 v13, 0, v64, s[40:41]
	s_cbranch_vccnz .LBB0_1683
	v_readlane_b32 s4, v100, 23
	s_nop 1
	v_mul_f32_e32 v13, s4, v13
.LBB0_1683:
	ds_write_b32 v47, v13 offset:5980
	s_and_b64 vcc, exec, s[42:43]
	s_waitcnt vmcnt(39)
	v_cndmask_b32_e64 v13, 0, v62, s[40:41]
	s_cbranch_vccnz .LBB0_1685
	v_readlane_b32 s4, v100, 24
	s_nop 1
	v_mul_f32_e32 v13, s4, v13
.LBB0_1685:
	ds_write_b32 v47, v13 offset:6240
	s_and_b64 vcc, exec, s[42:43]
	s_waitcnt vmcnt(38)
	v_cndmask_b32_e64 v13, 0, v60, s[40:41]
	s_cbranch_vccnz .LBB0_1687
	v_readlane_b32 s4, v100, 25
	s_nop 1
	v_mul_f32_e32 v13, s4, v13
.LBB0_1687:
	ds_write_b32 v47, v13 offset:6500
	s_and_b64 vcc, exec, s[42:43]
	s_waitcnt vmcnt(37)
	v_cndmask_b32_e64 v13, 0, v59, s[40:41]
	s_cbranch_vccnz .LBB0_1689
	v_readlane_b32 s4, v100, 26
	s_nop 1
	v_mul_f32_e32 v13, s4, v13
.LBB0_1689:
	ds_write_b32 v47, v13 offset:6760
	s_and_b64 vcc, exec, s[42:43]
	s_waitcnt vmcnt(36)
	v_cndmask_b32_e64 v13, 0, v58, s[40:41]
	s_cbranch_vccnz .LBB0_1691
	v_readlane_b32 s4, v100, 27
	s_nop 1
	v_mul_f32_e32 v13, s4, v13
.LBB0_1691:
	ds_write_b32 v47, v13 offset:7020
	s_and_b64 vcc, exec, s[42:43]
	s_waitcnt vmcnt(35)
	v_cndmask_b32_e64 v13, 0, v57, s[40:41]
	s_cbranch_vccnz .LBB0_1693
	v_readlane_b32 s4, v100, 28
	s_nop 1
	v_mul_f32_e32 v13, s4, v13
.LBB0_1693:
	ds_write_b32 v47, v13 offset:7280
	s_and_b64 vcc, exec, s[42:43]
	s_waitcnt vmcnt(34)
	v_cndmask_b32_e64 v13, 0, v44, s[40:41]
	s_cbranch_vccnz .LBB0_1695
	v_readlane_b32 s4, v100, 29
	s_nop 1
	v_mul_f32_e32 v13, s4, v13
.LBB0_1695:
	ds_write_b32 v47, v13 offset:7540
	s_and_b64 vcc, exec, s[42:43]
	s_waitcnt vmcnt(33)
	v_cndmask_b32_e64 v13, 0, v42, s[40:41]
	s_cbranch_vccnz .LBB0_1697
	v_readlane_b32 s4, v100, 30
	s_nop 1
	v_mul_f32_e32 v13, s4, v13
.LBB0_1697:
	ds_write_b32 v47, v13 offset:7800
	s_and_b64 vcc, exec, s[42:43]
	s_waitcnt vmcnt(32)
	v_cndmask_b32_e64 v13, 0, v45, s[40:41]
	s_cbranch_vccnz .LBB0_1699
	v_readlane_b32 s4, v100, 31
	s_nop 1
	v_mul_f32_e32 v13, s4, v13
.LBB0_1699:
	ds_write_b32 v47, v13 offset:8060
	s_and_b64 vcc, exec, s[42:43]
	s_waitcnt vmcnt(31)
	v_cndmask_b32_e64 v13, 0, v43, s[40:41]
	s_cbranch_vccnz .LBB0_1701
	v_readlane_b32 s4, v100, 32
	s_nop 1
	v_mul_f32_e32 v13, s4, v13
.LBB0_1701:
	ds_write_b32 v47, v13 offset:8320
	s_and_b64 vcc, exec, s[42:43]
	s_waitcnt vmcnt(30)
	v_cndmask_b32_e64 v13, 0, v41, s[40:41]
	s_cbranch_vccnz .LBB0_1703
	v_readlane_b32 s4, v100, 33
	s_nop 1
	v_mul_f32_e32 v13, s4, v13
.LBB0_1703:
	ds_write_b32 v47, v13 offset:8580
	s_and_b64 vcc, exec, s[42:43]
	s_waitcnt vmcnt(29)
	v_cndmask_b32_e64 v13, 0, v40, s[40:41]
	s_cbranch_vccnz .LBB0_1705
	v_readlane_b32 s4, v100, 34
	s_nop 1
	v_mul_f32_e32 v13, s4, v13
.LBB0_1705:
	ds_write_b32 v47, v13 offset:8840
	s_and_b64 vcc, exec, s[42:43]
	s_waitcnt vmcnt(28)
	v_cndmask_b32_e64 v13, 0, v39, s[40:41]
	s_cbranch_vccnz .LBB0_1707
	v_readlane_b32 s4, v100, 35
	s_nop 1
	v_mul_f32_e32 v13, s4, v13
.LBB0_1707:
	ds_write_b32 v47, v13 offset:9100
	s_and_b64 vcc, exec, s[42:43]
	s_waitcnt vmcnt(27)
	v_cndmask_b32_e64 v13, 0, v38, s[40:41]
	s_cbranch_vccnz .LBB0_1709
	v_readlane_b32 s4, v100, 36
	s_nop 1
	v_mul_f32_e32 v13, s4, v13
.LBB0_1709:
	ds_write_b32 v47, v13 offset:9360
	s_and_b64 vcc, exec, s[42:43]
	s_waitcnt vmcnt(26)
	v_cndmask_b32_e64 v13, 0, v36, s[40:41]
	s_cbranch_vccnz .LBB0_1711
	v_readlane_b32 s4, v100, 37
	s_nop 1
	v_mul_f32_e32 v13, s4, v13
.LBB0_1711:
	ds_write_b32 v47, v13 offset:9620
	s_and_b64 vcc, exec, s[42:43]
	s_waitcnt vmcnt(25)
	v_cndmask_b32_e64 v13, 0, v34, s[40:41]
	s_cbranch_vccnz .LBB0_1713
	v_readlane_b32 s4, v100, 38
	s_nop 1
	v_mul_f32_e32 v13, s4, v13
.LBB0_1713:
	ds_write_b32 v47, v13 offset:9880
	s_and_b64 vcc, exec, s[42:43]
	s_waitcnt vmcnt(24)
	v_cndmask_b32_e64 v13, 0, v37, s[40:41]
	s_cbranch_vccnz .LBB0_1715
	v_readlane_b32 s4, v100, 39
	s_nop 1
	v_mul_f32_e32 v13, s4, v13
.LBB0_1715:
	ds_write_b32 v47, v13 offset:10140
	s_and_b64 vcc, exec, s[42:43]
	s_waitcnt vmcnt(23)
	v_cndmask_b32_e64 v13, 0, v35, s[40:41]
	s_cbranch_vccnz .LBB0_1717
	v_readlane_b32 s4, v100, 40
	s_nop 1
	v_mul_f32_e32 v13, s4, v13
.LBB0_1717:
	ds_write_b32 v47, v13 offset:10400
	s_and_b64 vcc, exec, s[42:43]
	s_waitcnt vmcnt(22)
	v_cndmask_b32_e64 v13, 0, v33, s[40:41]
	s_cbranch_vccnz .LBB0_1719
	v_readlane_b32 s4, v100, 41
	s_nop 1
	v_mul_f32_e32 v13, s4, v13
.LBB0_1719:
	ds_write_b32 v47, v13 offset:10660
	s_and_b64 vcc, exec, s[42:43]
	s_waitcnt vmcnt(21)
	v_cndmask_b32_e64 v13, 0, v32, s[40:41]
	s_cbranch_vccnz .LBB0_1721
	v_readlane_b32 s4, v100, 42
	s_nop 1
	v_mul_f32_e32 v13, s4, v13
.LBB0_1721:
	ds_write_b32 v47, v13 offset:10920
	s_and_b64 vcc, exec, s[42:43]
	s_waitcnt vmcnt(20)
	v_cndmask_b32_e64 v13, 0, v31, s[40:41]
	s_cbranch_vccnz .LBB0_1723
	v_readlane_b32 s4, v100, 43
	s_nop 1
	v_mul_f32_e32 v13, s4, v13
.LBB0_1723:
	ds_write_b32 v47, v13 offset:11180
	s_and_b64 vcc, exec, s[42:43]
	s_waitcnt vmcnt(19)
	v_cndmask_b32_e64 v13, 0, v30, s[40:41]
	s_cbranch_vccnz .LBB0_1725
	v_readlane_b32 s4, v100, 44
	s_nop 1
	v_mul_f32_e32 v13, s4, v13
.LBB0_1725:
	ds_write_b32 v47, v13 offset:11440
	s_and_b64 vcc, exec, s[42:43]
	s_waitcnt vmcnt(18)
	v_cndmask_b32_e64 v13, 0, v28, s[40:41]
	s_cbranch_vccnz .LBB0_1727
	v_readlane_b32 s4, v100, 45
	s_nop 1
	v_mul_f32_e32 v13, s4, v13
.LBB0_1727:
	ds_write_b32 v47, v13 offset:11700
	s_and_b64 vcc, exec, s[42:43]
	s_waitcnt vmcnt(17)
	v_cndmask_b32_e64 v13, 0, v26, s[40:41]
	s_cbranch_vccnz .LBB0_1729
	v_readlane_b32 s4, v100, 46
	s_nop 1
	v_mul_f32_e32 v13, s4, v13
.LBB0_1729:
	ds_write_b32 v47, v13 offset:11960
	s_and_b64 vcc, exec, s[42:43]
	s_waitcnt vmcnt(16)
	v_cndmask_b32_e64 v13, 0, v29, s[40:41]
	s_cbranch_vccnz .LBB0_1731
	v_readlane_b32 s4, v100, 47
	s_nop 1
	v_mul_f32_e32 v13, s4, v13
.LBB0_1731:
	ds_write_b32 v47, v13 offset:12220
	s_and_b64 vcc, exec, s[42:43]
	s_waitcnt vmcnt(15)
	v_cndmask_b32_e64 v13, 0, v27, s[40:41]
	s_cbranch_vccnz .LBB0_1733
	v_readlane_b32 s4, v100, 48
	s_nop 1
	v_mul_f32_e32 v13, s4, v13
.LBB0_1733:
	ds_write_b32 v47, v13 offset:12480
	s_and_b64 vcc, exec, s[42:43]
	s_waitcnt vmcnt(14)
	v_cndmask_b32_e64 v13, 0, v25, s[40:41]
	s_cbranch_vccnz .LBB0_1735
	v_readlane_b32 s4, v100, 49
	s_nop 1
	v_mul_f32_e32 v13, s4, v13
.LBB0_1735:
	ds_write_b32 v47, v13 offset:12740
	s_and_b64 vcc, exec, s[42:43]
	s_waitcnt vmcnt(13)
	v_cndmask_b32_e64 v13, 0, v24, s[40:41]
	s_cbranch_vccnz .LBB0_1737
	v_readlane_b32 s4, v100, 50
	s_nop 1
	v_mul_f32_e32 v13, s4, v13
.LBB0_1737:
	ds_write_b32 v47, v13 offset:13000
	s_and_b64 vcc, exec, s[42:43]
	s_waitcnt vmcnt(12)
	v_cndmask_b32_e64 v13, 0, v23, s[40:41]
	s_cbranch_vccnz .LBB0_1739
	v_readlane_b32 s4, v100, 51
	s_nop 1
	v_mul_f32_e32 v13, s4, v13
.LBB0_1739:
	ds_write_b32 v47, v13 offset:13260
	s_and_b64 vcc, exec, s[42:43]
	s_waitcnt vmcnt(11)
	v_cndmask_b32_e64 v13, 0, v22, s[40:41]
	s_cbranch_vccnz .LBB0_1741
	v_readlane_b32 s4, v100, 52
	s_nop 1
	v_mul_f32_e32 v13, s4, v13
.LBB0_1741:
	ds_write_b32 v47, v13 offset:13520
	s_and_b64 vcc, exec, s[42:43]
	s_waitcnt vmcnt(10)
	v_cndmask_b32_e64 v13, 0, v20, s[40:41]
	s_cbranch_vccnz .LBB0_1743
	v_readlane_b32 s4, v100, 53
	s_nop 1
	v_mul_f32_e32 v13, s4, v13
.LBB0_1743:
	ds_write_b32 v47, v13 offset:13780
	s_and_b64 vcc, exec, s[42:43]
	s_waitcnt vmcnt(9)
	v_cndmask_b32_e64 v13, 0, v18, s[40:41]
	s_cbranch_vccnz .LBB0_1745
	v_readlane_b32 s4, v100, 54
	s_nop 1
	v_mul_f32_e32 v13, s4, v13
.LBB0_1745:
	ds_write_b32 v47, v13 offset:14040
	s_and_b64 vcc, exec, s[42:43]
	s_waitcnt vmcnt(8)
	v_cndmask_b32_e64 v13, 0, v21, s[40:41]
	s_cbranch_vccnz .LBB0_1747
	v_readlane_b32 s4, v100, 55
	s_nop 1
	v_mul_f32_e32 v13, s4, v13
.LBB0_1747:
	ds_write_b32 v47, v13 offset:14300
	s_and_b64 vcc, exec, s[42:43]
	s_waitcnt vmcnt(7)
	v_cndmask_b32_e64 v13, 0, v19, s[40:41]
	s_cbranch_vccnz .LBB0_1749
	v_readlane_b32 s4, v100, 56
	s_nop 1
	v_mul_f32_e32 v13, s4, v13
.LBB0_1749:
	ds_write_b32 v47, v13 offset:14560
	s_and_b64 vcc, exec, s[42:43]
	s_waitcnt vmcnt(6)
	v_cndmask_b32_e64 v13, 0, v17, s[40:41]
	s_cbranch_vccnz .LBB0_1751
	v_readlane_b32 s4, v100, 57
	s_nop 1
	v_mul_f32_e32 v13, s4, v13
.LBB0_1751:
	ds_write_b32 v47, v13 offset:14820
	s_and_b64 vcc, exec, s[42:43]
	s_waitcnt vmcnt(5)
	v_cndmask_b32_e64 v13, 0, v16, s[40:41]
	s_cbranch_vccnz .LBB0_1753
	v_readlane_b32 s4, v100, 58
	s_nop 1
	v_mul_f32_e32 v13, s4, v13
.LBB0_1753:
	ds_write_b32 v47, v13 offset:15080
	s_and_b64 vcc, exec, s[42:43]
	s_waitcnt vmcnt(4)
	v_cndmask_b32_e64 v13, 0, v15, s[40:41]
	s_cbranch_vccnz .LBB0_1755
	v_readlane_b32 s4, v100, 59
	s_nop 1
	v_mul_f32_e32 v13, s4, v13
.LBB0_1755:
	ds_write_b32 v47, v13 offset:15340
	s_and_b64 vcc, exec, s[42:43]
	s_waitcnt vmcnt(0)
	v_cndmask_b32_e64 v13, 0, v14, s[40:41]
	s_cbranch_vccnz .LBB0_1757
	v_readlane_b32 s4, v100, 60
	s_nop 1
	v_mul_f32_e32 v13, s4, v13
